# EpiRes phases: touch the tile's bf16 residual block (4 one-dword loads per wave) before its K-loop so the epilogue's residual reads hit cache
# baseline (speedup 1.0000x reference)
;     __device__ __forceinline__ void operator()(const f32x4 (&acc)[2][2][4][2], const Unit& u, int wr, int wc, int fr, int fq, PG8_LAS unsigned char* lds, int& rs_pm, int& rs_tog) const {
;         const int row0 = u.pm * BM + wr * 64 + fr, col0 = u.pn * BM + wc * 32 + 8 * fq;
;         u32x4 pre[4][2][2];
; template <class Epi, class Sched, bool ALIGN_EPI = false, bool SP2 = false>
; __device__ __forceinline__ void gemm_phase(PG8_LAS unsigned char* lds, const Gemm g, const Sched& S, const Epi& E) {
;     ...
;     for (;;) {
;         const bool has_next = S.next(ui + 1, nxt);
;         const char* nA = has_next ? (const char*)g.A + (size_t)nxt.pm * tstep : cA; const char* nB = has_next ? (const char*)g.Bt + (size_t)nxt.pn * tstep : cB;
;         for (int t = 0; t < nt; t += 2) {
;             const bool last = (t == nt - 2);
;             const char* a1 = cA + (size_t)(t + 1) * kstep;
;             const char* a2 = last ? nA : cA + (size_t)(t + 2) * kstep; const char* b2 = last ? nB : cB + (size_t)(t + 2) * kstep;
.LBB0_273:
	s_lshl_b32 s100, s33, 19
	s_lshl_b32 s101, s29, 9
	s_add_u32 s100, s100, s101
	s_add_u32 s100, s70, s100
	s_addc_u32 s101, s71, 0
	v_lshrrev_b32_e32 v255, 6, v230
	v_lshlrev_b32_e32 v255, 16, v255
	v_bfe_u32 v248, v230, 3, 3
	v_lshl_or_b32 v255, v248, 11, v255
	v_and_b32_e32 v248, 7, v230
	v_lshl_or_b32 v255, v248, 6, v255
	global_load_dword v248, v255, s[100:101]
	s_add_u32 s100, s100, 0x4000
	s_addc_u32 s101, s101, 0
	global_load_dword v249, v255, s[100:101]
	s_add_u32 s100, s100, 0x4000
	s_addc_u32 s101, s101, 0
	global_load_dword v250, v255, s[100:101]
	s_add_u32 s100, s100, 0x4000
	s_addc_u32 s101, s101, 0
	global_load_dword v251, v255, s[100:101]
	s_add_u32 s48, s48, 0x80
	s_addc_u32 s49, s49, 0
	s_add_u32 s50, s46, 0x100
	s_addc_u32 s51, s47, 0
	s_mov_b32 s46, 0

; __global__ void __launch_bounds__(NTHREADS, 2) fwd_megakernel(Args args) {
	.amdhsa_kernel _Z14fwd_megakernel4Args
		.amdhsa_group_segment_fixed_size 0
		.amdhsa_private_segment_fixed_size 0
		.amdhsa_kernarg_size 408
		.amdhsa_user_sgpr_count 2
		.amdhsa_user_sgpr_dispatch_ptr 0
		.amdhsa_user_sgpr_queue_ptr 0
		.amdhsa_user_sgpr_kernarg_segment_ptr 1
		.amdhsa_user_sgpr_dispatch_id 0
		.amdhsa_user_sgpr_kernarg_preload_length 0
		.amdhsa_user_sgpr_kernarg_preload_offset 0
		.amdhsa_user_sgpr_private_segment_size 0
		.amdhsa_uses_dynamic_stack 0
		.amdhsa_enable_private_segment 0
		.amdhsa_system_sgpr_workgroup_id_x 1
		.amdhsa_system_sgpr_workgroup_id_y 0
		.amdhsa_system_sgpr_workgroup_id_z 0
		.amdhsa_system_sgpr_workgroup_info 0
		.amdhsa_system_vgpr_workitem_id 2
		.amdhsa_next_free_vgpr 256
		.amdhsa_next_free_sgpr 102
		.amdhsa_accum_offset 256
		.amdhsa_reserve_vcc 1
		.amdhsa_float_round_mode_32 0
		.amdhsa_float_round_mode_16_64 0
		.amdhsa_float_denorm_mode_32 3
		.amdhsa_float_denorm_mode_16_64 3
		.amdhsa_dx10_clamp 1
		.amdhsa_ieee_mode 1
		.amdhsa_fp16_overflow 0
		.amdhsa_tg_split 0
		.amdhsa_exception_fp_ieee_invalid_op 0
		.amdhsa_exception_fp_denorm_src 0
		.amdhsa_exception_fp_ieee_div_zero 0
		.amdhsa_exception_fp_ieee_overflow 0
		.amdhsa_exception_fp_ieee_underflow 0
		.amdhsa_exception_fp_ieee_inexact 0
		.amdhsa_exception_int_div_zero 0
	.end_amdhsa_kernel

; __global__ void __launch_bounds__(NTHREADS, 2) fwd_megakernel(Args args) {
amdhsa.kernels:
  - .agpr_count:     0
    .args:
      - .offset:         0
        .size:           152
        .value_kind:     by_value
      - .offset:         152
        .size:           4
        .value_kind:     hidden_block_count_x
      - .offset:         156
        .size:           4
        .value_kind:     hidden_block_count_y
      - .offset:         160
        .size:           4
        .value_kind:     hidden_block_count_z
      - .offset:         164
        .size:           2
        .value_kind:     hidden_group_size_x
      - .offset:         166
        .size:           2
        .value_kind:     hidden_group_size_y
      - .offset:         168
        .size:           2
        .value_kind:     hidden_group_size_z
      - .offset:         170
        .size:           2
        .value_kind:     hidden_remainder_x
      - .offset:         172
        .size:           2
        .value_kind:     hidden_remainder_y
      - .offset:         174
        .size:           2
        .value_kind:     hidden_remainder_z
      - .offset:         192
        .size:           8
        .value_kind:     hidden_global_offset_x
      - .offset:         200
        .size:           8
        .value_kind:     hidden_global_offset_y
      - .offset:         208
        .size:           8
        .value_kind:     hidden_global_offset_z
      - .offset:         216
        .size:           2
        .value_kind:     hidden_grid_dims
      - .offset:         240
        .size:           8
        .value_kind:     hidden_multigrid_sync_arg
      - .offset:         272
        .size:           4
        .value_kind:     hidden_dynamic_lds_size
    .group_segment_fixed_size: 0
    .kernarg_segment_align: 8
    .kernarg_segment_size: 408
    .language:       OpenCL C
    .language_version:
      - 2
      - 0
    .max_flat_workgroup_size: 512
    .name:           _Z14fwd_megakernel4Args
    .private_segment_fixed_size: 0
    .sgpr_count:     108
    .sgpr_spill_count: 146
    .symbol:         _Z14fwd_megakernel4Args.kd
    .uniform_work_group_size: 1
    .uses_dynamic_stack: false
    .vgpr_count:     256
    .vgpr_spill_count: 0
    .wavefront_size: 64
